# NSA compressed unit pass 1: cross-half row max via v_permlane32_swap instead of ds_bpermute + wait
# baseline (speedup 1.0000x reference)
; DI int crow(int i, int h) { return (i & 3) + 8 * (i >> 2) + 4 * h; }
; DI void nsa_cmp_unit(const Params& p, int u, char* smem) {
;     ...
;       float mx = -1e30f;
; #pragma unroll
;       for (int i = 0; i < 16; ++i) { const bool valid = (32 * T + crow(i, h)) < nc; const float v = valid ? s[i] : -1e30f; s[i] = v; mx = fmaxf(mx, v); }
;       mx = fmaxf(mx, __shfl_xor(mx, 32));
;       const float mn = fmaxf(m, mx); float ps = 0.f;
; #pragma unroll
;       for (int i = 0; i < 16; ++i) ps += s[i] > -5e29f ? __expf(s[i] - mn) : 0.f;
;       l = l * __expf(m - mn) + ps; m = mn;
;     }
.LBB0_435:
	s_mov_b32 s9, 0xf149f2ca
	v_mov_b32_e32 v56, v140
	s_add_i32 s8, s8, -1
	s_waitcnt lgkmcnt(0)
	v_mfma_f32_32x32x16_bf16 v[34:49], v[234:237], v[102:105], 0
	s_cmp_lg_u32 s8, 0
	v_mfma_f32_32x32x16_bf16 v[34:49], v[238:241], v[98:101], v[34:49]
	v_mfma_f32_32x32x16_bf16 v[34:49], v[242:245], v[106:109], v[34:49]
	v_add_u32_e32 v51, 0x1200, v51
	v_mfma_f32_32x32x16_bf16 v[34:49], v[246:249], v[110:113], v[34:49]
	ds_read_b128 v[234:237], v51
	ds_read_b128 v[238:241], v51 offset:32
	ds_read_b128 v[242:245], v51 offset:64
	ds_read_b128 v[246:249], v51 offset:96
	v_subrev_u32_e32 v52, 27, v50
	v_cmp_lt_i32_e32 vcc, v52, v116
	v_subrev_u32_e32 v52, 26, v50
	v_subrev_u32_e32 v53, 25, v50
	s_nop 7
	v_cndmask_b32_e32 v34, v206, v34, vcc
	v_cmp_lt_i32_e32 vcc, v52, v116
	s_nop 1
	v_cndmask_b32_e32 v35, v206, v35, vcc
	v_cmp_lt_i32_e32 vcc, v53, v116
	v_subrev_u32_e32 v53, 24, v50
	v_max3_f32 v52, v34, s9, v35
	v_cndmask_b32_e32 v36, v206, v36, vcc
	v_cmp_lt_i32_e32 vcc, v53, v116
	v_subrev_u32_e32 v53, 19, v50
	s_nop 0
	v_cndmask_b32_e32 v37, v206, v37, vcc
	v_cmp_lt_i32_e32 vcc, v53, v116
	v_subrev_u32_e32 v53, 18, v50
	v_max3_f32 v52, v52, v36, v37
	v_cndmask_b32_e32 v38, v206, v38, vcc
	v_cmp_lt_i32_e32 vcc, v53, v116
	v_subrev_u32_e32 v53, 17, v50
	s_nop 0
	v_cndmask_b32_e32 v39, v206, v39, vcc
	v_cmp_lt_i32_e32 vcc, v53, v116
	v_add_u32_e32 v53, -16, v50
	v_max3_f32 v52, v52, v38, v39
	v_cndmask_b32_e32 v40, v206, v40, vcc
	v_cmp_lt_i32_e32 vcc, v53, v116
	v_add_u32_e32 v53, -11, v50
	s_nop 0
	v_cndmask_b32_e32 v41, v206, v41, vcc
	v_cmp_lt_i32_e32 vcc, v53, v116
	v_add_u32_e32 v53, -10, v50
	v_max3_f32 v52, v52, v40, v41
	v_cndmask_b32_e32 v42, v206, v42, vcc
	v_cmp_lt_i32_e32 vcc, v53, v116
	v_add_u32_e32 v53, -9, v50
	s_nop 0
	v_cndmask_b32_e32 v43, v206, v43, vcc
	v_cmp_lt_i32_e32 vcc, v53, v116
	v_add_u32_e32 v53, -8, v50
	v_max3_f32 v52, v52, v42, v43
	v_cndmask_b32_e32 v44, v206, v44, vcc
	v_cmp_lt_i32_e32 vcc, v53, v116
	v_add_u32_e32 v53, -3, v50
	s_nop 0
	v_cndmask_b32_e32 v45, v206, v45, vcc
	v_cmp_lt_i32_e32 vcc, v53, v116
	v_add_u32_e32 v53, -2, v50
	v_max3_f32 v52, v52, v44, v45
	v_cndmask_b32_e32 v46, v206, v46, vcc
	v_cmp_lt_i32_e32 vcc, v53, v116
	v_add_u32_e32 v53, -1, v50
	s_nop 0
	v_cndmask_b32_e32 v47, v206, v47, vcc
	v_cmp_lt_i32_e32 vcc, v53, v116
	v_max3_f32 v52, v52, v46, v47
	s_nop 0
	v_cndmask_b32_e32 v48, v206, v48, vcc
	v_cmp_lt_i32_e32 vcc, v50, v116
	v_add_u32_e32 v50, 32, v50
	s_nop 0
	v_cndmask_b32_e32 v49, v206, v49, vcc
	v_max3_f32 v52, v52, v48, v49
	v_mov_b32_e32 v53, v52
	v_mov_b32_e32 v250, v52
	v_cmp_lt_f32_e32 vcc, s60, v34
	s_nop 0
	v_permlane32_swap_b32_e32 v53, v250
	v_max3_f32 v140, v56, v53, v250
	v_sub_f32_e32 v34, v34, v140
	v_mul_f32_e32 v34, 0x3fb8aa3b, v34
	v_exp_f32_e32 v34, v34
	s_nop 0
	v_add_f32_e32 v34, 0, v34
	v_cndmask_b32_e32 v34, 0, v34, vcc
	v_cmp_lt_f32_e32 vcc, s60, v35
	v_sub_f32_e32 v35, v35, v140
	v_mul_f32_e32 v35, 0x3fb8aa3b, v35
	v_exp_f32_e32 v35, v35
	s_nop 0
	v_cndmask_b32_e32 v35, 0, v35, vcc
	v_add_f32_e32 v34, v35, v34
	v_sub_f32_e32 v35, v36, v140
	v_mul_f32_e32 v35, 0x3fb8aa3b, v35
	v_exp_f32_e32 v35, v35
	v_cmp_lt_f32_e32 vcc, s60, v36
	v_mov_b32_e32 v36, v0
	s_nop 0
	v_cndmask_b32_e32 v35, 0, v35, vcc
	v_add_f32_e32 v34, v35, v34
	v_sub_f32_e32 v35, v37, v140
	v_mul_f32_e32 v35, 0x3fb8aa3b, v35
	v_exp_f32_e32 v35, v35
	v_cmp_lt_f32_e32 vcc, s60, v37
	s_nop 1
	v_cndmask_b32_e32 v35, 0, v35, vcc
	v_add_f32_e32 v34, v35, v34
	v_sub_f32_e32 v35, v38, v140
	v_mul_f32_e32 v35, 0x3fb8aa3b, v35
	v_exp_f32_e32 v35, v35
	v_cmp_lt_f32_e32 vcc, s60, v38
	s_nop 1
	v_cndmask_b32_e32 v35, 0, v35, vcc
	v_add_f32_e32 v34, v35, v34
	v_sub_f32_e32 v35, v39, v140
	v_mul_f32_e32 v35, 0x3fb8aa3b, v35
	v_exp_f32_e32 v35, v35
	v_cmp_lt_f32_e32 vcc, s60, v39
	s_nop 1
	v_cndmask_b32_e32 v35, 0, v35, vcc
	v_add_f32_e32 v34, v35, v34
	v_sub_f32_e32 v35, v40, v140
	v_mul_f32_e32 v35, 0x3fb8aa3b, v35
	v_exp_f32_e32 v35, v35
	v_cmp_lt_f32_e32 vcc, s60, v40
	s_nop 1
	v_cndmask_b32_e32 v35, 0, v35, vcc
	v_add_f32_e32 v34, v35, v34
	v_sub_f32_e32 v35, v41, v140
	v_mul_f32_e32 v35, 0x3fb8aa3b, v35
	v_exp_f32_e32 v35, v35
	v_cmp_lt_f32_e32 vcc, s60, v41
	s_nop 1
	v_cndmask_b32_e32 v35, 0, v35, vcc
	v_add_f32_e32 v34, v35, v34
	v_sub_f32_e32 v35, v42, v140
	v_mul_f32_e32 v35, 0x3fb8aa3b, v35
	v_exp_f32_e32 v35, v35
	v_cmp_lt_f32_e32 vcc, s60, v42
	s_nop 1
	v_cndmask_b32_e32 v35, 0, v35, vcc
	v_add_f32_e32 v34, v35, v34
	v_sub_f32_e32 v35, v43, v140
	v_mul_f32_e32 v35, 0x3fb8aa3b, v35
	v_exp_f32_e32 v35, v35
	v_cmp_lt_f32_e32 vcc, s60, v43
	s_nop 1
	v_cndmask_b32_e32 v35, 0, v35, vcc
	v_add_f32_e32 v34, v35, v34
	v_sub_f32_e32 v35, v44, v140
	v_mul_f32_e32 v35, 0x3fb8aa3b, v35
	v_exp_f32_e32 v35, v35
	v_cmp_lt_f32_e32 vcc, s60, v44
	s_nop 1
	v_cndmask_b32_e32 v35, 0, v35, vcc
	v_add_f32_e32 v34, v35, v34
	v_sub_f32_e32 v35, v45, v140
	v_mul_f32_e32 v35, 0x3fb8aa3b, v35
	v_exp_f32_e32 v35, v35
	v_cmp_lt_f32_e32 vcc, s60, v45
	s_nop 1
	v_cndmask_b32_e32 v35, 0, v35, vcc
	v_add_f32_e32 v34, v35, v34
	v_sub_f32_e32 v35, v46, v140
	v_mul_f32_e32 v35, 0x3fb8aa3b, v35
	v_exp_f32_e32 v35, v35
	v_cmp_lt_f32_e32 vcc, s60, v46
	s_nop 1
	v_cndmask_b32_e32 v35, 0, v35, vcc
	v_add_f32_e32 v34, v35, v34
	v_sub_f32_e32 v35, v47, v140
	v_mul_f32_e32 v35, 0x3fb8aa3b, v35
	v_exp_f32_e32 v35, v35
	v_cmp_lt_f32_e32 vcc, s60, v47
	s_nop 1
	v_cndmask_b32_e32 v35, 0, v35, vcc
	v_add_f32_e32 v34, v35, v34
	v_sub_f32_e32 v35, v48, v140
	v_mul_f32_e32 v35, 0x3fb8aa3b, v35
	v_exp_f32_e32 v35, v35
	v_cmp_lt_f32_e32 vcc, s60, v48
	s_nop 1
	v_cndmask_b32_e32 v35, 0, v35, vcc
	v_add_f32_e32 v34, v35, v34
	v_sub_f32_e32 v35, v49, v140
	v_mul_f32_e32 v35, 0x3fb8aa3b, v35
	v_exp_f32_e32 v35, v35
	v_cmp_lt_f32_e32 vcc, s60, v49
	s_nop 1
	v_cndmask_b32_e32 v35, 0, v35, vcc
	v_add_f32_e32 v34, v35, v34
	v_sub_f32_e32 v35, v56, v140
	v_mul_f32_e32 v35, 0x3fb8aa3b, v35
	v_exp_f32_e32 v35, v35
	v_mov_b32_e32 v0, v34
	v_fmac_f32_e32 v0, v36, v35
	s_cbranch_scc1 .LBB0_435
